# NSA selected-branch loop: tile-list entry for the next iterations read one iteration ahead (no LDS round trip at the loop head)
# speedup vs baseline: 1.0076x; 1.0040x over previous
.LBB0_740:
	s_or_b64 exec, exec, s[6:7]
	v_readlane_b32 s6, v248, 12
	s_waitcnt lgkmcnt(0)
	s_barrier
	s_mov_b32 s79, s95
	v_mov_b32_e32 v0, s6
	ds_read_b32 v2, v0
	v_mov_b32_e32 v0, 0
	v_mov_b32_e32 v4, 0
	v_mov_b32_e32 v8, 0
	v_mov_b32_e32 v12, 0
	s_waitcnt lgkmcnt(0)
	v_readfirstlane_b32 s94, v2
	v_bfe_u32 v2, v101, 1, 1
	s_cmp_lt_i32 s94, 1
	v_or_b32_e32 v195, v99, v2
	v_bitop3_b32 v197, v99, v193, v2 bitop3:0x36
	v_bitop3_b32 v196, v99, v194, v2 bitop3:0x36
	v_mov_b32_e32 v80, 0
	v_mov_b32_e32 v84, 0
	v_mov_b32_e32 v88, 0
	v_mov_b32_e32 v92, 0
	v_mov_b32_e32 v96, 0
	v_mov_b32_e32 v100, 0
	v_mov_b32_e32 v105, 0
	v_mov_b32_e32 v109, 0
	v_mov_b32_e32 v208, 0
	v_mov_b32_e32 v212, 0
	v_mov_b32_e32 v216, 0
	v_mov_b32_e32 v220, 0
	v_mov_b32_e32 v2, 0
	v_mov_b32_e32 v6, 0
	v_mov_b32_e32 v10, 0
	v_mov_b32_e32 v14, 0
	v_mov_b32_e32 v82, 0
	v_mov_b32_e32 v86, 0
	v_mov_b32_e32 v90, 0
	v_mov_b32_e32 v94, 0
	v_mov_b32_e32 v98, 0
	v_mov_b32_e32 v103, 0
	v_mov_b32_e32 v107, 0
	v_mov_b32_e32 v111, 0
	v_mov_b32_e32 v210, 0
	v_mov_b32_e32 v214, 0
	v_mov_b32_e32 v218, 0
	v_mov_b32_e32 v222, 0
	v_mov_b32_e32 v3, 0
	v_mov_b32_e32 v7, 0
	v_mov_b32_e32 v11, 0
	v_mov_b32_e32 v15, 0
	v_mov_b32_e32 v83, 0
	v_mov_b32_e32 v87, 0
	v_mov_b32_e32 v91, 0
	v_mov_b32_e32 v95, 0
	v_mov_b32_e32 v99, 0
	v_mov_b32_e32 v104, 0
	v_mov_b32_e32 v108, 0
	v_mov_b32_e32 v207, 0
	v_mov_b32_e32 v211, 0
	v_mov_b32_e32 v215, 0
	v_mov_b32_e32 v219, 0
	v_mov_b32_e32 v223, 0
	v_mov_b32_e32 v5, 0
	v_mov_b32_e32 v9, 0
	v_mov_b32_e32 v13, 0
	v_mov_b32_e32 v81, 0
	v_mov_b32_e32 v85, 0
	v_mov_b32_e32 v89, 0
	v_mov_b32_e32 v93, 0
	v_mov_b32_e32 v97, 0
	v_mov_b32_e32 v102, 0
	v_mov_b32_e32 v106, 0
	v_mov_b32_e32 v110, 0
	v_mov_b32_e32 v209, 0
	v_mov_b32_e32 v213, 0
	v_mov_b32_e32 v217, 0
	v_mov_b32_e32 v221, 0
	v_mov_b32_e32 v224, 0
	v_mov_b32_e32 v198, 0
	s_cbranch_scc1 .LBB0_752
	v_readlane_b32 s6, v248, 40
	v_readlane_b32 s7, v248, 41
	s_lshl_b64 s[6:7], s[6:7], 1
	s_add_u32 s8, s2, s6
	s_addc_u32 s9, s3, s7
	s_add_u32 s6, s8, 0x1b000000
	s_addc_u32 s7, s9, 0
	s_add_u32 s8, s8, 0x1a000000
	s_addc_u32 s9, s9, 0
	s_add_i32 s10, 0, 0x18820
	v_mov_b32_e32 v0, s10
	ds_read_b32 v2, v0
	v_and_b32_e32 v0, 28, v101
	s_mov_b32 m0, s0
	v_lshl_add_u32 v0, v0, 2, s44
	s_mov_b64 s[10:11], 0x2000
	s_waitcnt lgkmcnt(0)
	v_ashrrev_i32_e32 v3, 31, v2
	v_lshlrev_b64 v[2:3], 14, v[2:3]
	v_lshl_add_u64 v[4:5], s[8:9], 0, v[2:3]
	v_lshl_add_u64 v[4:5], v[4:5], 0, v[156:157]
	ds_read_b128 v[144:147], v0
	global_load_lds_dwordx4 v[4:5], off
	v_lshl_add_u64 v[4:5], v[4:5], 0, s[10:11]
	s_mov_b32 m0, s80
	v_lshl_add_u64 v[2:3], s[6:7], 0, v[2:3]
	global_load_lds_dwordx4 v[4:5], off
	v_lshl_add_u64 v[2:3], v[2:3], 0, v[156:157]
	s_mov_b32 m0, s81
	v_or_b32_e32 v0, s84, v187
	global_load_lds_dwordx4 v[2:3], off
	v_lshl_add_u64 v[2:3], v[2:3], 0, s[10:11]
	s_mov_b32 m0, s85
	v_lshl_add_u64 v[158:159], s[8:9], 0, v[156:157]
	global_load_lds_dwordx4 v[2:3], off
	v_or_b32_e32 v2, 32, v0
	v_cmp_gt_i32_e64 s[8:9], v2, v152
	v_or_b32_e32 v2, 33, v0
	v_cmp_gt_i32_e64 s[12:13], v2, v152
	v_or_b32_e32 v2, 2, v0
	v_or_b32_e32 v3, 34, v0
	v_cmp_gt_i32_e64 s[14:15], v2, v152
	v_or_b32_e32 v2, 3, v0
	v_cmp_gt_i32_e64 s[16:17], v3, v152
	v_or_b32_e32 v3, 35, v0
	v_cmp_gt_i32_e64 s[18:19], v2, v152
	v_or_b32_e32 v2, 8, v0
	v_cmp_gt_i32_e64 s[20:21], v3, v152
	v_or_b32_e32 v3, 40, v0
	v_cmp_gt_i32_e64 s[22:23], v2, v152
	v_or_b32_e32 v2, 9, v0
	v_cmp_gt_i32_e64 s[24:25], v3, v152
	v_or_b32_e32 v3, 41, v0
	v_cmp_gt_i32_e64 s[26:27], v2, v152
	v_or_b32_e32 v2, 10, v0
	v_cmp_gt_i32_e64 s[28:29], v3, v152
	v_or_b32_e32 v3, 42, v0
	v_cmp_gt_i32_e64 s[30:31], v2, v152
	v_or_b32_e32 v2, 11, v0
	v_cmp_gt_i32_e64 s[34:35], v3, v152
	v_or_b32_e32 v3, 43, v0
	v_cmp_gt_i32_e64 s[36:37], v2, v152
	v_or_b32_e32 v2, 16, v0
	v_cmp_gt_i32_e64 s[38:39], v3, v152
	v_or_b32_e32 v3, 48, v0
	v_cmp_gt_i32_e64 s[40:41], v2, v152
	v_or_b32_e32 v2, 17, v0
	v_cmp_gt_i32_e64 s[42:43], v3, v152
	v_or_b32_e32 v3, 49, v0
	v_cmp_gt_i32_e64 s[44:45], v2, v152
	v_or_b32_e32 v2, 18, v0
	v_cmp_gt_i32_e64 s[46:47], v3, v152
	v_or_b32_e32 v3, 50, v0
	v_cmp_gt_i32_e64 s[48:49], v2, v152
	v_or_b32_e32 v2, 19, v0
	v_cmp_gt_i32_e64 s[50:51], v3, v152
	v_or_b32_e32 v3, 51, v0
	v_cmp_gt_i32_e64 s[52:53], v2, v152
	v_or_b32_e32 v2, 24, v0
	v_cmp_gt_i32_e64 s[54:55], v3, v152
	v_or_b32_e32 v3, 56, v0
	v_cmp_gt_i32_e64 s[56:57], v2, v152
	v_or_b32_e32 v2, 25, v0
	v_cmp_gt_i32_e64 s[58:59], v3, v152
	v_or_b32_e32 v3, 57, v0
	v_cmp_gt_i32_e64 s[60:61], v2, v152
	v_or_b32_e32 v2, 26, v0
	v_lshl_add_u64 v[160:161], s[6:7], 0, v[156:157]
	v_cmp_gt_i32_e64 s[6:7], v0, v152
	v_cmp_lt_i32_e64 s[10:11], v0, v152
	v_cmp_gt_i32_e64 s[62:63], v3, v152
	v_or_b32_e32 v3, 58, v0
	v_cmp_gt_i32_e64 s[64:65], v2, v152
	v_or_b32_e32 v2, 27, v0
	v_or_b32_e32 v0, 59, v0
	v_cmp_gt_i32_e64 s[70:71], v0, v152
	v_bitop3_b32 v0, v195, v193, 4 bitop3:0x36
	v_lshlrev_b32_e32 v201, 4, v0
	v_bitop3_b32 v0, v195, v194, 4 bitop3:0x36
	v_lshlrev_b32_e32 v202, 4, v0
	v_bitop3_b32 v0, v195, v193, 8 bitop3:0x36
	v_lshlrev_b32_e32 v203, 4, v0
	v_bitop3_b32 v0, v195, v194, 8 bitop3:0x36
	v_lshlrev_b32_e32 v204, 4, v0
	v_bitop3_b32 v0, v195, v193, 12 bitop3:0x36
	s_waitcnt vmcnt(0) lgkmcnt(0)
	s_barrier
	v_lshlrev_b32_e32 v205, 4, v0
	v_bitop3_b32 v0, v195, v194, 12 bitop3:0x36
	v_mov_b32_e32 v14, v1
	v_mov_b32_e32 v15, v1
	v_cmp_gt_i32_e64 s[66:67], v3, v152
	v_cmp_gt_i32_e64 s[68:69], v2, v152
	v_lshlrev_b32_e32 v206, 4, v0
	v_mov_b32_e32 v0, v1
	v_mov_b32_e32 v2, v1
	v_mov_b32_e32 v3, v1
	v_mov_b32_e32 v4, v1
	v_mov_b32_e32 v5, v1
	v_mov_b32_e32 v6, v1
	v_mov_b32_e32 v7, v1
	v_mov_b32_e32 v8, v1
	v_mov_b32_e32 v9, v1
	v_mov_b32_e32 v10, v1
	v_mov_b32_e32 v11, v1
	v_mov_b32_e32 v12, v1
	v_mov_b32_e32 v13, v1
	v_mov_b64_e32 v[30:31], v[14:15]
	v_mov_b64_e32 v[46:47], v[14:15]
	v_mov_b64_e32 v[62:63], v[14:15]
	v_mov_b64_e32 v[78:79], v[14:15]
	s_mov_b32 s82, s74
	s_mov_b64 s[74:75], s[90:91]
	v_lshlrev_b32_e32 v199, 4, v197
	v_lshlrev_b32_e32 v200, 4, v196
	s_mov_b32 s95, 0
	v_mov_b32_e32 v198, 0
	v_readlane_b32 s90, v248, 13
	v_mov_b64_e32 v[28:29], v[12:13]
	v_mov_b64_e32 v[26:27], v[10:11]
	v_mov_b64_e32 v[24:25], v[8:9]
	v_mov_b64_e32 v[22:23], v[6:7]
	v_mov_b64_e32 v[20:21], v[4:5]
	v_mov_b64_e32 v[18:19], v[2:3]
	v_mov_b64_e32 v[16:17], v[0:1]
	v_mov_b64_e32 v[44:45], v[12:13]
	v_mov_b64_e32 v[42:43], v[10:11]
	v_mov_b64_e32 v[40:41], v[8:9]
	v_mov_b64_e32 v[38:39], v[6:7]
	v_mov_b64_e32 v[36:37], v[4:5]
	v_mov_b64_e32 v[34:35], v[2:3]
	v_mov_b64_e32 v[32:33], v[0:1]
	v_mov_b64_e32 v[60:61], v[12:13]
	v_mov_b64_e32 v[58:59], v[10:11]
	v_mov_b64_e32 v[56:57], v[8:9]
	v_mov_b64_e32 v[54:55], v[6:7]
	v_mov_b64_e32 v[52:53], v[4:5]
	v_mov_b64_e32 v[50:51], v[2:3]
	v_mov_b64_e32 v[48:49], v[0:1]
	v_mov_b64_e32 v[76:77], v[12:13]
	v_mov_b64_e32 v[74:75], v[10:11]
	v_mov_b64_e32 v[72:73], v[8:9]
	v_mov_b64_e32 v[70:71], v[6:7]
	v_mov_b64_e32 v[68:69], v[4:5]
	v_mov_b64_e32 v[66:67], v[2:3]
	v_mov_b64_e32 v[64:65], v[0:1]
	v_mov_b32_e32 v224, 0
	v_mov_b32_e32 v221, 0
	v_mov_b32_e32 v217, 0
	v_mov_b32_e32 v213, 0
	v_mov_b32_e32 v209, 0
	v_mov_b32_e32 v110, 0
	v_mov_b32_e32 v106, 0
	v_mov_b32_e32 v102, 0
	v_mov_b32_e32 v97, 0
	v_mov_b32_e32 v93, 0
	v_mov_b32_e32 v89, 0
	v_mov_b32_e32 v85, 0
	v_mov_b32_e32 v81, 0
	v_mov_b32_e32 v13, 0
	v_mov_b32_e32 v9, 0
	v_mov_b32_e32 v5, 0
	v_mov_b32_e32 v223, 0
	v_mov_b32_e32 v219, 0
	v_mov_b32_e32 v215, 0
	v_mov_b32_e32 v211, 0
	v_mov_b32_e32 v207, 0
	v_mov_b32_e32 v108, 0
	v_mov_b32_e32 v104, 0
	v_mov_b32_e32 v99, 0
	v_mov_b32_e32 v95, 0
	v_mov_b32_e32 v91, 0
	v_mov_b32_e32 v87, 0
	v_mov_b32_e32 v83, 0
	v_mov_b32_e32 v15, 0
	v_mov_b32_e32 v11, 0
	v_mov_b32_e32 v7, 0
	v_mov_b32_e32 v3, 0
	v_mov_b32_e32 v222, 0
	v_mov_b32_e32 v218, 0
	v_mov_b32_e32 v214, 0
	v_mov_b32_e32 v210, 0
	v_mov_b32_e32 v111, 0
	v_mov_b32_e32 v107, 0
	v_mov_b32_e32 v103, 0
	v_mov_b32_e32 v98, 0
	v_mov_b32_e32 v94, 0
	v_mov_b32_e32 v90, 0
	v_mov_b32_e32 v86, 0
	v_mov_b32_e32 v82, 0
	v_mov_b32_e32 v14, 0
	v_mov_b32_e32 v10, 0
	v_mov_b32_e32 v6, 0
	v_mov_b32_e32 v2, 0
	v_mov_b32_e32 v220, 0
	v_mov_b32_e32 v216, 0
	v_mov_b32_e32 v212, 0
	v_mov_b32_e32 v208, 0
	v_mov_b32_e32 v109, 0
	v_mov_b32_e32 v105, 0
	v_mov_b32_e32 v100, 0
	v_mov_b32_e32 v96, 0
	v_mov_b32_e32 v92, 0
	v_mov_b32_e32 v88, 0
	v_mov_b32_e32 v84, 0
	v_mov_b32_e32 v80, 0
	v_mov_b32_e32 v12, 0
	v_mov_b32_e32 v8, 0
	v_mov_b32_e32 v4, 0
	v_mov_b32_e32 v0, 0
	s_add_i32 s72, s90, -4
	v_mov_b32_e32 v101, s72
	ds_read2_b32 v[220:221], v101 offset1:1
	s_waitcnt lgkmcnt(0)
	s_branch .LBB0_744

.LBB0_743:
	s_waitcnt vmcnt(0) lgkmcnt(0)
	v_mov_b32_e32 v220, v221
	v_mov_b32_e32 v221, v222
	s_barrier
	s_add_i32 s90, s90, 4
	s_cmp_lg_u32 s94, s95
	s_cbranch_scc0 .LBB0_751
.LBB0_744:
	s_add_i32 s72, s90, 4
	v_mov_b32_e32 v101, s72
	ds_read_b32 v222, v101
	s_and_b32 s91, s95, 1
	s_add_i32 s95, s95, 1
	s_cmp_ge_i32 s95, s94
	v_readfirstlane_b32 s92, v220
	s_cbranch_scc1 .LBB0_746
	v_mov_b32_e32 v226, v221
	s_lshl_b32 s72, s91, 14
	s_xor_b32 s72, s72, 0x4000
	s_add_i32 s72, s0, s72
	s_mov_b32 m0, s72
	v_ashrrev_i32_e32 v227, 31, v226
	v_lshlrev_b64 v[226:227], 14, v[226:227]
	v_lshl_add_u64 v[228:229], v[158:159], 0, v[226:227]
	s_mov_b64 s[76:77], 0x2000
	global_load_lds_dwordx4 v[228:229], off
	v_lshl_add_u64 v[228:229], v[228:229], 0, s[76:77]
	s_add_i32 m0, s72, 0x2000
	v_lshl_add_u64 v[226:227], v[160:161], 0, v[226:227]
	global_load_lds_dwordx4 v[228:229], off
	s_add_i32 m0, s72, 0x8000
	s_nop 0
	global_load_lds_dwordx4 v[226:227], off
	v_lshl_add_u64 v[226:227], v[226:227], 0, s[76:77]
	s_add_i32 m0, s72, 0xa000
	s_nop 0
	global_load_lds_dwordx4 v[226:227], off
